# merge gate GEMM: 3 LDS stages (two k-steps of LDS-DMA in flight), +16KB static LDS
# speedup vs baseline: 1.0830x; 1.0342x over previous
.LBB0_732:
	v_mov_b32_e32 v20, v198
	s_ashr_i32 s3, s2, 31
	s_lshl_b64 s[12:13], s[2:3], 11
	v_ashrrev_i32_e32 v21, 6, v20
	v_bfe_u32 v0, v20, 3, 3
	s_lshl_b32 s3, s52, 10
	v_lshl_or_b32 v0, v21, 3, v0
	s_add_i32 s54, s3, s6
	v_lshrrev_b32_e32 v23, 1, v0
	s_ashr_i32 s55, s54, 31
	v_xor_b32_e32 v6, v23, v20
	v_ashrrev_i32_e32 v1, 31, v0
	s_lshl_b64 s[54:55], s[54:55], 11
	v_lshlrev_b64 v[2:3], 11, v[0:1]
	v_lshlrev_b32_e32 v1, 4, v6
	v_add_u32_e32 v6, 64, v0
	v_add_u32_e32 v10, 0x80, v0
	v_add_u32_e32 v0, 0xc0, v0
	s_add_u32 s54, s16, s54
	v_and_b32_e32 v64, 0x70, v1
	v_ashrrev_i32_e32 v7, 31, v6
	v_ashrrev_i32_e32 v11, 31, v10
	v_ashrrev_i32_e32 v1, 31, v0
	s_addc_u32 s55, s17, s55
	v_lshlrev_b64 v[6:7], 11, v[6:7]
	v_lshlrev_b64 v[10:11], 11, v[10:11]
	v_lshlrev_b64 v[0:1], 11, v[0:1]
	v_lshl_add_u64 v[4:5], s[8:9], 0, v[2:3]
	v_lshl_add_u64 v[8:9], s[8:9], 0, v[6:7]
	v_lshl_add_u64 v[12:13], s[8:9], 0, v[10:11]
	v_lshl_add_u64 v[14:15], s[8:9], 0, v[0:1]
	v_lshl_add_u64 v[16:17], s[54:55], 0, v[2:3]
	v_lshl_add_u64 v[18:19], s[54:55], 0, v[6:7]
	v_lshl_add_u64 v[4:5], v[4:5], 0, v[64:65]
	v_lshl_add_u64 v[8:9], v[8:9], 0, v[64:65]
	v_lshl_add_u64 v[12:13], v[12:13], 0, v[64:65]
	v_lshl_add_u64 v[14:15], v[14:15], 0, v[64:65]
	v_lshl_add_u64 v[16:17], v[16:17], 0, v[64:65]
	v_lshl_add_u64 v[18:19], v[18:19], 0, v[64:65]
	v_lshl_add_u32 v64, v21, 10, 0
	v_bfe_u32 v24, v20, 4, 2
	v_readfirstlane_b32 s3, v64
	s_mov_b32 m0, s3
	v_bfe_u32 v25, v20, 1, 3
	global_load_lds_dwordx4 v[4:5], off
	v_add_u32_e32 v4, 0x2000, v64
	s_add_u32 s12, s23, s12
	v_readfirstlane_b32 s3, v4
	v_add_u32_e32 v4, 0x4000, v64
	s_mov_b32 m0, s3
	v_readfirstlane_b32 s3, v4
	v_add_u32_e32 v4, 0x6000, v64
	global_load_lds_dwordx4 v[8:9], off
	s_mov_b32 m0, s3
	v_readfirstlane_b32 s3, v4
	v_add_u32_e32 v4, 0x8000, v64
	global_load_lds_dwordx4 v[12:13], off
	s_mov_b32 m0, s3
	v_readfirstlane_b32 s3, v4
	v_add_u32_e32 v4, 0xa000, v64
	global_load_lds_dwordx4 v[14:15], off
	s_mov_b32 m0, s3
	v_readfirstlane_b32 s3, v4
	global_load_lds_dwordx4 v[16:17], off
	s_mov_b32 m0, s3
	v_lshrrev_b32_e32 v4, 31, v20
	global_load_lds_dwordx4 v[18:19], off
	v_add_u32_e32 v4, v21, v4
	v_and_b32_e32 v5, 0x7fffe, v4
	v_lshlrev_b32_e32 v4, 12, v4
	v_and_b32_e32 v144, 0xffffe000, v4
	v_xor_b32_e32 v4, v24, v25
	v_lshlrev_b32_e32 v145, 4, v4
	v_bitop3_b32 v4, v24, v25, 4 bitop3:0x36
	v_lshlrev_b32_e32 v146, 4, v4
	v_bitop3_b32 v4, v23, 7, v20 bitop3:0x48
	s_waitcnt vmcnt(0)
	v_lshlrev_b32_e32 v4, 4, v4
	v_and_b32_e32 v22, 15, v20
	v_sub_u32_e32 v5, v21, v5
	v_or_b32_e32 v2, v2, v4
	v_or_b32_e32 v6, v6, v4
	v_or_b32_e32 v10, v10, v4
	v_or_b32_e32 v0, v0, v4
	s_addc_u32 s13, s24, s13
	v_mov_b32_e32 v8, 0
	v_lshlrev_b32_e32 v142, 13, v5
	v_lshlrev_b32_e32 v143, 7, v22
	v_lshl_add_u64 v[130:131], s[10:11], 0, v[2:3]
	v_lshl_add_u64 v[132:133], s[10:11], 0, v[6:7]
	v_lshl_add_u64 v[134:135], s[10:11], 0, v[10:11]
	v_lshl_add_u64 v[136:137], s[10:11], 0, v[0:1]
	v_lshl_add_u64 v[138:139], s[12:13], 0, v[2:3]
	v_lshl_add_u64 v[140:141], s[12:13], 0, v[6:7]
	s_mov_b64 s[12:13], 0
	s_mov_b32 s3, 0
	v_mov_b32_e32 v9, v8
	v_mov_b32_e32 v10, v8
	v_mov_b32_e32 v11, v8
	v_mov_b32_e32 v0, v8
	v_mov_b32_e32 v1, v8
	v_mov_b32_e32 v2, v8
	v_mov_b32_e32 v3, v8
	v_mov_b32_e32 v4, v8
	v_mov_b32_e32 v5, v8
	v_mov_b32_e32 v6, v8
	v_mov_b32_e32 v7, v8
	v_mov_b32_e32 v12, v8
	v_mov_b32_e32 v13, v8
	v_mov_b32_e32 v14, v8
	v_mov_b32_e32 v15, v8
	v_mov_b32_e32 v16, v8
	v_mov_b32_e32 v17, v8
	v_mov_b32_e32 v18, v8
	v_mov_b32_e32 v19, v8
	v_mov_b32_e32 v20, v8
	v_mov_b32_e32 v21, v8
	v_mov_b32_e32 v22, v8
	v_mov_b32_e32 v23, v8
	v_mov_b32_e32 v24, v8
	v_mov_b32_e32 v25, v8
	v_mov_b32_e32 v26, v8
	v_mov_b32_e32 v27, v8
	v_mov_b32_e32 v28, v8
	v_mov_b32_e32 v29, v8
	v_mov_b32_e32 v30, v8
	v_mov_b32_e32 v31, v8
	v_mov_b32_e32 v32, v8
	v_mov_b32_e32 v33, v8
	v_mov_b32_e32 v34, v8
	v_mov_b32_e32 v35, v8
	v_mov_b32_e32 v36, v8
	v_mov_b32_e32 v37, v8
	v_mov_b32_e32 v38, v8
	v_mov_b32_e32 v39, v8
	v_mov_b32_e32 v40, v8
	v_mov_b32_e32 v41, v8
	v_mov_b32_e32 v42, v8
	v_mov_b32_e32 v43, v8
	v_mov_b32_e32 v44, v8
	v_mov_b32_e32 v45, v8
	v_mov_b32_e32 v46, v8
	v_mov_b32_e32 v47, v8
	v_mov_b32_e32 v48, v8
	v_mov_b32_e32 v49, v8
	v_mov_b32_e32 v50, v8
	v_mov_b32_e32 v51, v8
	v_mov_b32_e32 v52, v8
	v_mov_b32_e32 v53, v8
	v_mov_b32_e32 v54, v8
	v_mov_b32_e32 v55, v8
	v_mov_b32_e32 v56, v8
	v_mov_b32_e32 v57, v8
	v_mov_b32_e32 v58, v8
	v_mov_b32_e32 v59, v8
	v_mov_b32_e32 v60, v8
	v_mov_b32_e32 v61, v8
	v_mov_b32_e32 v62, v8
	v_mov_b32_e32 v63, v8
	v_readfirstlane_b32 s54, v64
	s_nop 1
	s_add_i32 s54, s54, 0xc000
	s_mov_b32 m0, s54
	s_nop 0
	global_load_lds_dwordx4 v[130:131], off
	s_add_i32 m0, s54, 0x2000
	s_nop 0
	global_load_lds_dwordx4 v[132:133], off
	s_add_i32 m0, s54, 0x4000
	s_nop 0
	global_load_lds_dwordx4 v[134:135], off
	s_add_i32 m0, s54, 0x6000
	s_nop 0
	global_load_lds_dwordx4 v[136:137], off
	s_add_i32 m0, s54, 0x8000
	s_nop 0
	global_load_lds_dwordx4 v[138:139], off
	s_add_i32 m0, s54, 0xa000
	s_nop 0
	global_load_lds_dwordx4 v[140:141], off
	s_waitcnt vmcnt(6) lgkmcnt(0)
	s_barrier
	s_branch .LBB0_734
.LBB0_733:
	v_readfirstlane_b32 s54, v64
	s_add_i32 m0, s53, 2
	s_cmp_ge_u32 m0, 3
	s_cbranch_scc0 .Lg3a_gemm7
	s_sub_u32 m0, m0, 3
.Lg3a_gemm7:
	s_mul_i32 m0, m0, 0xc000
	s_add_i32 s54, s54, m0
	s_mul_i32 s53, s53, 0xc000
	s_add_i32 s53, s53, 0
	v_add3_u32 v147, s53, v142, v143
	v_add_u32_e32 v168, v147, v145
	v_add3_u32 v172, s53, v144, v143
	v_add_u32_e32 v173, v172, v145
	ds_read_b128 v[148:151], v168 offset:32768
	ds_read_b128 v[152:155], v168 offset:34816
	ds_read_b128 v[164:167], v168 offset:36864
	ds_read_b128 v[168:171], v168 offset:38912
	ds_read_b128 v[156:159], v173
	ds_read_b128 v[160:163], v173 offset:2048
	ds_read_b128 v[242:245], v173 offset:4096
	ds_read_b128 v[246:249], v173 offset:6144
	s_add_u32 s12, s12, 0x80
	s_addc_u32 s13, s13, 0
	s_mov_b32 m0, s54
	v_lshl_add_u64 v[254:255], v[130:131], 0, s[12:13]
	global_load_lds_dwordx4 v[254:255], off
	s_add_i32 m0, s54, 0x2000
	v_lshl_add_u64 v[254:255], v[132:133], 0, s[12:13]
	global_load_lds_dwordx4 v[254:255], off
	s_waitcnt lgkmcnt(2)
	v_mfma_f32_16x16x32_bf16 v[60:63], v[148:151], v[156:159], v[60:63]
	v_add_u32_e32 v147, v147, v146
	v_add_u32_e32 v172, v172, v146
	v_mfma_f32_16x16x32_bf16 v[44:47], v[148:151], v[160:163], v[44:47]
	v_mfma_f32_16x16x32_bf16 v[56:59], v[152:155], v[156:159], v[56:59]
	v_mfma_f32_16x16x32_bf16 v[40:43], v[152:155], v[160:163], v[40:43]
	s_add_i32 m0, s54, 0x4000
	v_lshl_add_u64 v[254:255], v[134:135], 0, s[12:13]
	global_load_lds_dwordx4 v[254:255], off
	v_mfma_f32_16x16x32_bf16 v[52:55], v[164:167], v[156:159], v[52:55]
	v_mfma_f32_16x16x32_bf16 v[36:39], v[164:167], v[160:163], v[36:39]
	v_mfma_f32_16x16x32_bf16 v[48:51], v[168:171], v[156:159], v[48:51]
	v_mfma_f32_16x16x32_bf16 v[32:35], v[168:171], v[160:163], v[32:35]
	s_add_i32 m0, s54, 0x6000
	v_lshl_add_u64 v[254:255], v[136:137], 0, s[12:13]
	global_load_lds_dwordx4 v[254:255], off
	ds_read_b128 v[156:159], v172
	ds_read_b128 v[160:163], v172 offset:2048
	s_waitcnt lgkmcnt(2)
	v_mfma_f32_16x16x32_bf16 v[28:31], v[148:151], v[242:245], v[28:31]
	v_mfma_f32_16x16x32_bf16 v[12:15], v[148:151], v[246:249], v[12:15]
	ds_read_b128 v[148:151], v147 offset:32768
	v_mfma_f32_16x16x32_bf16 v[24:27], v[152:155], v[242:245], v[24:27]
	v_mfma_f32_16x16x32_bf16 v[4:7], v[152:155], v[246:249], v[4:7]
	s_add_i32 m0, s54, 0x8000
	v_lshl_add_u64 v[254:255], v[138:139], 0, s[12:13]
	global_load_lds_dwordx4 v[254:255], off
	ds_read_b128 v[152:155], v147 offset:34816
	v_mfma_f32_16x16x32_bf16 v[20:23], v[164:167], v[242:245], v[20:23]
	v_mfma_f32_16x16x32_bf16 v[0:3], v[164:167], v[246:249], v[0:3]
	ds_read_b128 v[164:167], v147 offset:36864
	v_mfma_f32_16x16x32_bf16 v[16:19], v[168:171], v[242:245], v[16:19]
	v_mfma_f32_16x16x32_bf16 v[8:11], v[168:171], v[246:249], v[8:11]
	s_add_i32 m0, s54, 0xa000
	v_lshl_add_u64 v[254:255], v[140:141], 0, s[12:13]
	global_load_lds_dwordx4 v[254:255], off
	s_add_i32 s3, s3, 1
	s_cmpk_lg_i32 s12, 0x800
	ds_read_b128 v[168:171], v147 offset:38912
	ds_read_b128 v[242:245], v172 offset:4096
	ds_read_b128 v[246:249], v172 offset:6144
	s_waitcnt lgkmcnt(2)
	v_mfma_f32_16x16x32_bf16 v[60:63], v[148:151], v[156:159], v[60:63]
	v_mfma_f32_16x16x32_bf16 v[44:47], v[148:151], v[160:163], v[44:47]
	v_mfma_f32_16x16x32_bf16 v[56:59], v[152:155], v[156:159], v[56:59]
	v_mfma_f32_16x16x32_bf16 v[40:43], v[152:155], v[160:163], v[40:43]
	v_mfma_f32_16x16x32_bf16 v[52:55], v[164:167], v[156:159], v[52:55]
	v_mfma_f32_16x16x32_bf16 v[36:39], v[164:167], v[160:163], v[36:39]
	v_mfma_f32_16x16x32_bf16 v[48:51], v[168:171], v[156:159], v[48:51]
	v_mfma_f32_16x16x32_bf16 v[32:35], v[168:171], v[160:163], v[32:35]
	s_cbranch_scc0 .Lg3l_gemm7
	s_waitcnt vmcnt(6) lgkmcnt(0)
	s_branch .Lg3j_gemm7
.Lg3l_gemm7:
	s_waitcnt vmcnt(0) lgkmcnt(0)
.Lg3j_gemm7:
	v_mfma_f32_16x16x32_bf16 v[28:31], v[148:151], v[242:245], v[28:31]
	s_barrier
	v_mfma_f32_16x16x32_bf16 v[12:15], v[148:151], v[246:249], v[12:15]
	v_mfma_f32_16x16x32_bf16 v[24:27], v[152:155], v[242:245], v[24:27]
	v_mfma_f32_16x16x32_bf16 v[4:7], v[152:155], v[246:249], v[4:7]
	v_mfma_f32_16x16x32_bf16 v[20:23], v[164:167], v[242:245], v[20:23]
	v_mfma_f32_16x16x32_bf16 v[0:3], v[164:167], v[246:249], v[0:3]
	v_mfma_f32_16x16x32_bf16 v[16:19], v[168:171], v[242:245], v[16:19]
	v_mfma_f32_16x16x32_bf16 v[8:11], v[168:171], v[246:249], v[8:11]
	s_cbranch_scc0 .LBB0_736
.LBB0_734:
	s_mul_hi_u32 s53, s3, 0x55555556
	s_mul_i32 s53, s53, 3
	s_sub_u32 s53, s3, s53
	s_branch .LBB0_733

.LBB0_1498:
	v_mov_b32_e32 v20, v198
	s_ashr_i32 s3, s2, 31
	s_lshl_b64 s[12:13], s[2:3], 11
	v_ashrrev_i32_e32 v21, 6, v20
	v_bfe_u32 v0, v20, 3, 3
	s_lshl_b32 s3, s44, 10
	v_lshl_or_b32 v0, v21, 3, v0
	s_add_i32 s46, s3, s6
	v_lshrrev_b32_e32 v23, 1, v0
	s_ashr_i32 s47, s46, 31
	v_xor_b32_e32 v6, v23, v20
	v_ashrrev_i32_e32 v1, 31, v0
	s_lshl_b64 s[46:47], s[46:47], 11
	v_lshlrev_b64 v[2:3], 11, v[0:1]
	v_lshlrev_b32_e32 v1, 4, v6
	v_add_u32_e32 v6, 64, v0
	v_add_u32_e32 v10, 0x80, v0
	v_add_u32_e32 v0, 0xc0, v0
	s_add_u32 s46, s16, s46
	v_and_b32_e32 v64, 0x70, v1
	v_ashrrev_i32_e32 v7, 31, v6
	v_ashrrev_i32_e32 v11, 31, v10
	v_ashrrev_i32_e32 v1, 31, v0
	s_addc_u32 s47, s17, s47
	v_lshlrev_b64 v[6:7], 11, v[6:7]
	v_lshlrev_b64 v[10:11], 11, v[10:11]
	v_lshlrev_b64 v[0:1], 11, v[0:1]
	v_lshl_add_u64 v[4:5], s[8:9], 0, v[2:3]
	v_lshl_add_u64 v[8:9], s[8:9], 0, v[6:7]
	v_lshl_add_u64 v[12:13], s[8:9], 0, v[10:11]
	v_lshl_add_u64 v[14:15], s[8:9], 0, v[0:1]
	v_lshl_add_u64 v[16:17], s[46:47], 0, v[2:3]
	v_lshl_add_u64 v[18:19], s[46:47], 0, v[6:7]
	v_lshl_add_u64 v[4:5], v[4:5], 0, v[64:65]
	v_lshl_add_u64 v[8:9], v[8:9], 0, v[64:65]
	v_lshl_add_u64 v[12:13], v[12:13], 0, v[64:65]
	v_lshl_add_u64 v[14:15], v[14:15], 0, v[64:65]
	v_lshl_add_u64 v[16:17], v[16:17], 0, v[64:65]
	v_lshl_add_u64 v[18:19], v[18:19], 0, v[64:65]
	v_lshl_add_u32 v64, v21, 10, 0
	v_bfe_u32 v24, v20, 4, 2
	v_readfirstlane_b32 s3, v64
	s_mov_b32 m0, s3
	v_bfe_u32 v25, v20, 1, 3
	global_load_lds_dwordx4 v[4:5], off
	v_add_u32_e32 v4, 0x2000, v64
	s_add_u32 s12, s23, s12
	v_readfirstlane_b32 s3, v4
	v_add_u32_e32 v4, 0x4000, v64
	s_mov_b32 m0, s3
	v_readfirstlane_b32 s3, v4
	v_add_u32_e32 v4, 0x6000, v64
	global_load_lds_dwordx4 v[8:9], off
	s_mov_b32 m0, s3
	v_readfirstlane_b32 s3, v4
	v_add_u32_e32 v4, 0x8000, v64
	global_load_lds_dwordx4 v[12:13], off
	s_mov_b32 m0, s3
	v_readfirstlane_b32 s3, v4
	v_add_u32_e32 v4, 0xa000, v64
	global_load_lds_dwordx4 v[14:15], off
	s_mov_b32 m0, s3
	v_readfirstlane_b32 s3, v4
	global_load_lds_dwordx4 v[16:17], off
	s_mov_b32 m0, s3
	v_lshrrev_b32_e32 v4, 31, v20
	global_load_lds_dwordx4 v[18:19], off
	v_add_u32_e32 v4, v21, v4
	v_and_b32_e32 v5, 0x7fffe, v4
	v_lshlrev_b32_e32 v4, 12, v4
	v_and_b32_e32 v144, 0xffffe000, v4
	v_xor_b32_e32 v4, v24, v25
	v_lshlrev_b32_e32 v145, 4, v4
	v_bitop3_b32 v4, v24, v25, 4 bitop3:0x36
	v_lshlrev_b32_e32 v146, 4, v4
	v_bitop3_b32 v4, v23, 7, v20 bitop3:0x48
	s_waitcnt vmcnt(0)
	v_lshlrev_b32_e32 v4, 4, v4
	v_and_b32_e32 v22, 15, v20
	v_sub_u32_e32 v5, v21, v5
	v_or_b32_e32 v2, v2, v4
	v_or_b32_e32 v6, v6, v4
	v_or_b32_e32 v10, v10, v4
	v_or_b32_e32 v0, v0, v4
	s_addc_u32 s13, s24, s13
	v_mov_b32_e32 v8, 0
	v_lshlrev_b32_e32 v142, 13, v5
	v_lshlrev_b32_e32 v143, 7, v22
	v_lshl_add_u64 v[130:131], s[10:11], 0, v[2:3]
	v_lshl_add_u64 v[132:133], s[10:11], 0, v[6:7]
	v_lshl_add_u64 v[134:135], s[10:11], 0, v[10:11]
	v_lshl_add_u64 v[136:137], s[10:11], 0, v[0:1]
	v_lshl_add_u64 v[138:139], s[12:13], 0, v[2:3]
	v_lshl_add_u64 v[140:141], s[12:13], 0, v[6:7]
	s_mov_b64 s[12:13], 0
	s_mov_b32 s3, 0
	v_mov_b32_e32 v9, v8
	v_mov_b32_e32 v10, v8
	v_mov_b32_e32 v11, v8
	v_mov_b32_e32 v0, v8
	v_mov_b32_e32 v1, v8
	v_mov_b32_e32 v2, v8
	v_mov_b32_e32 v3, v8
	v_mov_b32_e32 v4, v8
	v_mov_b32_e32 v5, v8
	v_mov_b32_e32 v6, v8
	v_mov_b32_e32 v7, v8
	v_mov_b32_e32 v12, v8
	v_mov_b32_e32 v13, v8
	v_mov_b32_e32 v14, v8
	v_mov_b32_e32 v15, v8
	v_mov_b32_e32 v16, v8
	v_mov_b32_e32 v17, v8
	v_mov_b32_e32 v18, v8
	v_mov_b32_e32 v19, v8
	v_mov_b32_e32 v20, v8
	v_mov_b32_e32 v21, v8
	v_mov_b32_e32 v22, v8
	v_mov_b32_e32 v23, v8
	v_mov_b32_e32 v24, v8
	v_mov_b32_e32 v25, v8
	v_mov_b32_e32 v26, v8
	v_mov_b32_e32 v27, v8
	v_mov_b32_e32 v28, v8
	v_mov_b32_e32 v29, v8
	v_mov_b32_e32 v30, v8
	v_mov_b32_e32 v31, v8
	v_mov_b32_e32 v32, v8
	v_mov_b32_e32 v33, v8
	v_mov_b32_e32 v34, v8
	v_mov_b32_e32 v35, v8
	v_mov_b32_e32 v36, v8
	v_mov_b32_e32 v37, v8
	v_mov_b32_e32 v38, v8
	v_mov_b32_e32 v39, v8
	v_mov_b32_e32 v40, v8
	v_mov_b32_e32 v41, v8
	v_mov_b32_e32 v42, v8
	v_mov_b32_e32 v43, v8
	v_mov_b32_e32 v44, v8
	v_mov_b32_e32 v45, v8
	v_mov_b32_e32 v46, v8
	v_mov_b32_e32 v47, v8
	v_mov_b32_e32 v48, v8
	v_mov_b32_e32 v49, v8
	v_mov_b32_e32 v50, v8
	v_mov_b32_e32 v51, v8
	v_mov_b32_e32 v52, v8
	v_mov_b32_e32 v53, v8
	v_mov_b32_e32 v54, v8
	v_mov_b32_e32 v55, v8
	v_mov_b32_e32 v56, v8
	v_mov_b32_e32 v57, v8
	v_mov_b32_e32 v58, v8
	v_mov_b32_e32 v59, v8
	v_mov_b32_e32 v60, v8
	v_mov_b32_e32 v61, v8
	v_mov_b32_e32 v62, v8
	v_mov_b32_e32 v63, v8
	v_readfirstlane_b32 s46, v64
	s_nop 1
	s_add_i32 s46, s46, 0xc000
	s_mov_b32 m0, s46
	s_nop 0
	global_load_lds_dwordx4 v[130:131], off
	s_add_i32 m0, s46, 0x2000
	s_nop 0
	global_load_lds_dwordx4 v[132:133], off
	s_add_i32 m0, s46, 0x4000
	s_nop 0
	global_load_lds_dwordx4 v[134:135], off
	s_add_i32 m0, s46, 0x6000
	s_nop 0
	global_load_lds_dwordx4 v[136:137], off
	s_add_i32 m0, s46, 0x8000
	s_nop 0
	global_load_lds_dwordx4 v[138:139], off
	s_add_i32 m0, s46, 0xa000
	s_nop 0
	global_load_lds_dwordx4 v[140:141], off
	s_waitcnt vmcnt(6) lgkmcnt(0)
	s_barrier
	s_branch .LBB0_1500
.LBB0_1499:
	v_readfirstlane_b32 s46, v64
	s_add_i32 m0, s45, 2
	s_cmp_ge_u32 m0, 3
	s_cbranch_scc0 .Lg3a_gemm2
	s_sub_u32 m0, m0, 3
.Lg3a_gemm2:
	s_mul_i32 m0, m0, 0xc000
	s_add_i32 s46, s46, m0
	s_mul_i32 s45, s45, 0xc000
	s_add_i32 s45, s45, 0
	v_add3_u32 v147, s45, v142, v143
	v_add_u32_e32 v168, v147, v145
	v_add3_u32 v172, s45, v144, v143
	v_add_u32_e32 v173, v172, v145
	ds_read_b128 v[148:151], v168 offset:32768
	ds_read_b128 v[152:155], v168 offset:34816
	ds_read_b128 v[164:167], v168 offset:36864
	ds_read_b128 v[168:171], v168 offset:38912
	ds_read_b128 v[156:159], v173
	ds_read_b128 v[160:163], v173 offset:2048
	ds_read_b128 v[242:245], v173 offset:4096
	ds_read_b128 v[246:249], v173 offset:6144
	s_add_u32 s12, s12, 0x80
	s_addc_u32 s13, s13, 0
	s_mov_b32 m0, s46
	v_lshl_add_u64 v[254:255], v[130:131], 0, s[12:13]
	global_load_lds_dwordx4 v[254:255], off
	s_add_i32 m0, s46, 0x2000
	v_lshl_add_u64 v[254:255], v[132:133], 0, s[12:13]
	global_load_lds_dwordx4 v[254:255], off
	s_waitcnt lgkmcnt(2)
	v_mfma_f32_16x16x32_bf16 v[60:63], v[148:151], v[156:159], v[60:63]
	v_add_u32_e32 v147, v147, v146
	v_add_u32_e32 v172, v172, v146
	v_mfma_f32_16x16x32_bf16 v[44:47], v[148:151], v[160:163], v[44:47]
	v_mfma_f32_16x16x32_bf16 v[56:59], v[152:155], v[156:159], v[56:59]
	v_mfma_f32_16x16x32_bf16 v[40:43], v[152:155], v[160:163], v[40:43]
	s_add_i32 m0, s46, 0x4000
	v_lshl_add_u64 v[254:255], v[134:135], 0, s[12:13]
	global_load_lds_dwordx4 v[254:255], off
	v_mfma_f32_16x16x32_bf16 v[52:55], v[164:167], v[156:159], v[52:55]
	v_mfma_f32_16x16x32_bf16 v[36:39], v[164:167], v[160:163], v[36:39]
	v_mfma_f32_16x16x32_bf16 v[48:51], v[168:171], v[156:159], v[48:51]
	v_mfma_f32_16x16x32_bf16 v[32:35], v[168:171], v[160:163], v[32:35]
	s_add_i32 m0, s46, 0x6000
	v_lshl_add_u64 v[254:255], v[136:137], 0, s[12:13]
	global_load_lds_dwordx4 v[254:255], off
	ds_read_b128 v[156:159], v172
	ds_read_b128 v[160:163], v172 offset:2048
	s_waitcnt lgkmcnt(2)
	v_mfma_f32_16x16x32_bf16 v[28:31], v[148:151], v[242:245], v[28:31]
	v_mfma_f32_16x16x32_bf16 v[12:15], v[148:151], v[246:249], v[12:15]
	ds_read_b128 v[148:151], v147 offset:32768
	v_mfma_f32_16x16x32_bf16 v[24:27], v[152:155], v[242:245], v[24:27]
	v_mfma_f32_16x16x32_bf16 v[4:7], v[152:155], v[246:249], v[4:7]
	s_add_i32 m0, s46, 0x8000
	v_lshl_add_u64 v[254:255], v[138:139], 0, s[12:13]
	global_load_lds_dwordx4 v[254:255], off
	ds_read_b128 v[152:155], v147 offset:34816
	v_mfma_f32_16x16x32_bf16 v[20:23], v[164:167], v[242:245], v[20:23]
	v_mfma_f32_16x16x32_bf16 v[0:3], v[164:167], v[246:249], v[0:3]
	ds_read_b128 v[164:167], v147 offset:36864
	v_mfma_f32_16x16x32_bf16 v[16:19], v[168:171], v[242:245], v[16:19]
	v_mfma_f32_16x16x32_bf16 v[8:11], v[168:171], v[246:249], v[8:11]
	s_add_i32 m0, s46, 0xa000
	v_lshl_add_u64 v[254:255], v[140:141], 0, s[12:13]
	global_load_lds_dwordx4 v[254:255], off
	s_add_i32 s3, s3, 1
	s_cmpk_lg_i32 s12, 0x800
	ds_read_b128 v[168:171], v147 offset:38912
	ds_read_b128 v[242:245], v172 offset:4096
	ds_read_b128 v[246:249], v172 offset:6144
	s_waitcnt lgkmcnt(2)
	v_mfma_f32_16x16x32_bf16 v[60:63], v[148:151], v[156:159], v[60:63]
	v_mfma_f32_16x16x32_bf16 v[44:47], v[148:151], v[160:163], v[44:47]
	v_mfma_f32_16x16x32_bf16 v[56:59], v[152:155], v[156:159], v[56:59]
	v_mfma_f32_16x16x32_bf16 v[40:43], v[152:155], v[160:163], v[40:43]
	v_mfma_f32_16x16x32_bf16 v[52:55], v[164:167], v[156:159], v[52:55]
	v_mfma_f32_16x16x32_bf16 v[36:39], v[164:167], v[160:163], v[36:39]
	v_mfma_f32_16x16x32_bf16 v[48:51], v[168:171], v[156:159], v[48:51]
	v_mfma_f32_16x16x32_bf16 v[32:35], v[168:171], v[160:163], v[32:35]
	s_cbranch_scc0 .Lg3l_gemm2
	s_waitcnt vmcnt(6) lgkmcnt(0)
	s_branch .Lg3j_gemm2

.LBB0_1500:
	s_mul_hi_u32 s45, s3, 0x55555556
	s_mul_i32 s45, s45, 3
	s_sub_u32 s45, s3, s45
	s_branch .LBB0_1499

	.amdhsa_kernel _Z14fwd_megakernel6Params
		.amdhsa_group_segment_fixed_size 16384
		.amdhsa_private_segment_fixed_size 0
		.amdhsa_kernarg_size 416
		.amdhsa_user_sgpr_count 2
		.amdhsa_user_sgpr_dispatch_ptr 0
		.amdhsa_user_sgpr_queue_ptr 0
		.amdhsa_user_sgpr_kernarg_segment_ptr 1
		.amdhsa_user_sgpr_dispatch_id 0
		.amdhsa_user_sgpr_kernarg_preload_length 0
		.amdhsa_user_sgpr_kernarg_preload_offset 0
		.amdhsa_user_sgpr_private_segment_size 0
		.amdhsa_uses_dynamic_stack 0
		.amdhsa_enable_private_segment 0
		.amdhsa_system_sgpr_workgroup_id_x 1
		.amdhsa_system_sgpr_workgroup_id_y 0
		.amdhsa_system_sgpr_workgroup_id_z 0
		.amdhsa_system_sgpr_workgroup_info 0
		.amdhsa_system_vgpr_workitem_id 2
		.amdhsa_next_free_vgpr 256
		.amdhsa_next_free_sgpr 102
		.amdhsa_accum_offset 256
		.amdhsa_reserve_vcc 1
		.amdhsa_float_round_mode_32 0
		.amdhsa_float_round_mode_16_64 0
		.amdhsa_float_denorm_mode_32 3
		.amdhsa_float_denorm_mode_16_64 3
		.amdhsa_dx10_clamp 1
		.amdhsa_ieee_mode 1
		.amdhsa_fp16_overflow 0
		.amdhsa_tg_split 0
		.amdhsa_exception_fp_ieee_invalid_op 0
		.amdhsa_exception_fp_denorm_src 0
		.amdhsa_exception_fp_ieee_div_zero 0
		.amdhsa_exception_fp_ieee_overflow 0
		.amdhsa_exception_fp_ieee_underflow 0
		.amdhsa_exception_fp_ieee_inexact 0
		.amdhsa_exception_int_div_zero 0
	.end_amdhsa_kernel

amdhsa.kernels:
  - .agpr_count:     0
    .args:
      - .offset:         0
        .size:           160
        .value_kind:     by_value
      - .offset:         160
        .size:           4
        .value_kind:     hidden_block_count_x
      - .offset:         164
        .size:           4
        .value_kind:     hidden_block_count_y
      - .offset:         168
        .size:           4
        .value_kind:     hidden_block_count_z
      - .offset:         172
        .size:           2
        .value_kind:     hidden_group_size_x
      - .offset:         174
        .size:           2
        .value_kind:     hidden_group_size_y
      - .offset:         176
        .size:           2
        .value_kind:     hidden_group_size_z
      - .offset:         178
        .size:           2
        .value_kind:     hidden_remainder_x
      - .offset:         180
        .size:           2
        .value_kind:     hidden_remainder_y
      - .offset:         182
        .size:           2
        .value_kind:     hidden_remainder_z
      - .offset:         200
        .size:           8
        .value_kind:     hidden_global_offset_x
      - .offset:         208
        .size:           8
        .value_kind:     hidden_global_offset_y
      - .offset:         216
        .size:           8
        .value_kind:     hidden_global_offset_z
      - .offset:         224
        .size:           2
        .value_kind:     hidden_grid_dims
      - .offset:         248
        .size:           8
        .value_kind:     hidden_multigrid_sync_arg
      - .offset:         280
        .size:           4
        .value_kind:     hidden_dynamic_lds_size
    .group_segment_fixed_size: 16384
    .kernarg_segment_align: 8
    .kernarg_segment_size: 416
    .language:       OpenCL C
    .language_version:
      - 2
      - 0
    .max_flat_workgroup_size: 512
    .name:           _Z14fwd_megakernel6Params
    .private_segment_fixed_size: 0
    .sgpr_count:     108
    .sgpr_spill_count: 65
    .symbol:         _Z14fwd_megakernel6Params.kd
    .uniform_work_group_size: 1
    .uses_dynamic_stack: false
    .vgpr_count:     256
    .vgpr_spill_count: 0
    .wavefront_size: 64
